# MV1b: as MV1 (last P.V MFMA group behind the X section's closing barrier) with the 4 MFMAs interleaved into the row-max chain at the head of the softmax section; on top of BE1
# baseline (speedup 1.0000x reference)
.LBB0_628:
	v_and_b32_e32 v5, 0x3fffffc0, v4
	s_add_i32 s8, 0, 0x18000
	v_lshl_add_u32 v171, v5, 2, s8
	s_add_i32 s8, 0, 0xc000
	s_cmp_lg_u32 s8, -1
	v_and_b32_e32 v169, 63, v4
	v_lshlrev_b32_e32 v4, 4, v4
	s_cselect_b32 s8, s8, 0
	v_and_b32_e32 v4, 0x70, v4
	v_lshl_add_u32 v7, v165, 8, s8
	v_or_b32_e32 v8, 32, v168
	v_xad_u32 v175, v8, v4, v7
	v_or_b32_e32 v8, 64, v168
	v_lshlrev_b32_e32 v5, 4, v169
	v_xad_u32 v176, v8, v4, v7
	v_or_b32_e32 v8, 0x60, v168
	s_mov_b32 s48, 2
	s_mov_b32 s49, 1
	v_lshlrev_b32_e32 v6, 1, v169
	s_mov_b32 s52, 0
	v_xad_u32 v174, v168, v4, v7
	v_xad_u32 v177, v8, v4, v7
	v_lshlrev_b32_e32 v66, 3, v169
	s_movk_i32 s50, 0xc0
	v_and_b32_e32 v67, 0xc0, v5
	v_and_b32_e32 v148, 32, v6
	ds_read_b128 v[4:7], v174 offset:0
	ds_read_b128 v[8:11], v174 offset:0x2000
	ds_read_b128 v[12:15], v175 offset:0
	ds_read_b128 v[42:45], v175 offset:0x2000
	ds_read_b128 v[46:49], v176 offset:0
	ds_read_b128 v[50:53], v176 offset:0x2000
	ds_read_b128 v[54:57], v177 offset:0
	ds_read_b128 v[58:61], v177 offset:0x2000
	s_waitcnt lgkmcnt(4)
	s_nop 0
	v_mfma_f32_32x32x16_bf16 v[84:99], v[4:7], v[128:131], 0
	s_mov_b32 s53, s52
	s_mov_b32 s54, s52
	s_mov_b32 s55, s52
	s_mov_b32 s56, s52
	s_mov_b32 s57, s52
	s_mov_b32 s58, s52
	s_mov_b32 s59, s52
	v_mfma_f32_32x32x16_bf16 v[68:83], v[8:11], v[128:131], 0
	s_mov_b32 s60, s52
	s_mov_b32 s61, s52
	s_mov_b32 s62, s52
	s_mov_b32 s63, s52
	s_mov_b32 s64, s52
	s_mov_b32 s65, s52
	s_mov_b32 s66, s52
	v_mfma_f32_32x32x16_bf16 v[84:99], v[12:15], v[124:127], v[84:99]
	s_mov_b32 s67, s52
	v_mov_b64_e32 v[4:5], s[52:53]
	v_mov_b64_e32 v[6:7], s[54:55]
	v_mov_b64_e32 v[8:9], s[56:57]
	v_mov_b64_e32 v[10:11], s[58:59]
	v_mov_b64_e32 v[12:13], s[60:61]
	v_mov_b64_e32 v[14:15], s[62:63]
	v_mfma_f32_32x32x16_bf16 v[68:83], v[42:45], v[124:127], v[68:83]
	v_mov_b64_e32 v[16:17], s[64:65]
	v_mov_b64_e32 v[18:19], s[66:67]
	ds_read_b128 v[42:45], v174 offset:0x80
	ds_read_b128 v[62:65], v174 offset:0x2080
	ds_read_b128 v[132:135], v175 offset:0x80
	ds_read_b128 v[136:139], v175 offset:0x2080
	s_waitcnt lgkmcnt(4)
	v_mfma_f32_32x32x16_bf16 v[84:99], v[46:49], v[120:123], v[84:99]
	v_mfma_f32_32x32x16_bf16 v[68:83], v[50:53], v[120:123], v[68:83]
	v_mfma_f32_32x32x16_bf16 v[84:99], v[54:57], v[116:119], v[84:99]
	v_mfma_f32_32x32x16_bf16 v[68:83], v[58:61], v[116:119], v[68:83]
	ds_read_b128 v[46:49], v176 offset:0x80
	ds_read_b128 v[50:53], v176 offset:0x2080
	ds_read_b128 v[54:57], v177 offset:0x80
	ds_read_b128 v[58:61], v177 offset:0x2080
	s_waitcnt lgkmcnt(4)
	v_mfma_f32_32x32x16_bf16 v[84:99], v[42:45], v[112:115], v[84:99]
	v_mfma_f32_32x32x16_bf16 v[68:83], v[62:65], v[112:115], v[68:83]
	v_mfma_f32_32x32x16_bf16 v[84:99], v[132:135], v[108:111], v[84:99]
	v_mfma_f32_32x32x16_bf16 v[68:83], v[136:139], v[108:111], v[68:83]
	s_waitcnt lgkmcnt(0)
	v_mfma_f32_32x32x16_bf16 v[84:99], v[46:49], v[104:107], v[84:99]
	v_mfma_f32_32x32x16_bf16 v[68:83], v[50:53], v[104:107], v[68:83]
	v_mfma_f32_32x32x16_bf16 v[84:99], v[54:57], v[100:103], v[84:99]
	v_mfma_f32_32x32x16_bf16 v[68:83], v[58:61], v[100:103], v[68:83]
	s_add_i32 s8, 0, 0x10000
	s_waitcnt vmcnt(0)
	s_waitcnt vmcnt(3)
	ds_write_b128 v40, v[20:23] offset:16384
	s_waitcnt vmcnt(2)
	ds_write_b128 v41, v[24:27] offset:16384
	v_add_u32_e32 v20, s8, v180
	s_waitcnt vmcnt(1)
	ds_write_b128 v20, v[28:31]
	v_add_u32_e32 v20, s8, v181
	s_waitcnt vmcnt(0)
	ds_write_b128 v20, v[32:35]
	v_add_co_u32_e32 v20, vcc, s22, v38
	s_nop 1
	v_addc_co_u32_e32 v21, vcc, 0, v39, vcc
	global_load_dwordx4 v[132:135], v[20:21], off
	v_add_co_u32_e32 v20, vcc, s24, v38
	s_nop 1
	v_addc_co_u32_e32 v21, vcc, 0, v39, vcc
	global_load_dwordx4 v[140:143], v[20:21], off
	v_add_co_u32_e32 v20, vcc, s22, v36
	s_nop 1
	v_addc_co_u32_e32 v21, vcc, 0, v37, vcc
	global_load_dwordx4 v[136:139], v[20:21], off
	v_add_co_u32_e32 v20, vcc, s24, v36
	s_nop 1
	v_addc_co_u32_e32 v21, vcc, 0, v37, vcc
	global_load_dwordx4 v[144:147], v[20:21], off
	s_waitcnt lgkmcnt(0)
	s_barrier
	s_movk_i32 s8, 0x118
	s_cmp_lg_u32 0, -1
	v_and_or_b32 v20, v66, s8, v148
	s_cselect_b32 s8, 0, 0
	v_add3_u32 v173, v67, s8, v20
	v_mov_b64_e32 v[66:67], v[18:19]
	v_mov_b64_e32 v[50:51], v[18:19]
	v_mov_b64_e32 v[34:35], v[18:19]
	v_cmp_gt_u32_e64 s[38:39], 32, v169
	v_lshl_add_u32 v172, v165, 2, v171
	v_mov_b32_e32 v183, 0
	v_mov_b32_e32 v182, 0xf149f2ca
	v_mov_b64_e32 v[64:65], v[16:17]
	v_mov_b64_e32 v[62:63], v[14:15]
	v_mov_b64_e32 v[60:61], v[12:13]
	v_mov_b64_e32 v[58:59], v[10:11]
	v_mov_b64_e32 v[56:57], v[8:9]
	v_mov_b64_e32 v[54:55], v[6:7]
	v_mov_b64_e32 v[52:53], v[4:5]
	v_mov_b64_e32 v[48:49], v[16:17]
	v_mov_b64_e32 v[46:47], v[14:15]
	v_mov_b64_e32 v[44:45], v[12:13]
	v_mov_b64_e32 v[42:43], v[10:11]
	v_mov_b64_e32 v[40:41], v[8:9]
	v_mov_b64_e32 v[38:39], v[6:7]
	v_mov_b64_e32 v[36:37], v[4:5]
	v_mov_b64_e32 v[32:33], v[16:17]
	v_mov_b64_e32 v[30:31], v[14:15]
	v_mov_b64_e32 v[28:29], v[12:13]
	v_mov_b64_e32 v[26:27], v[10:11]
	v_mov_b64_e32 v[24:25], v[8:9]
	v_mov_b64_e32 v[22:23], v[6:7]
	v_mov_b64_e32 v[20:21], v[4:5]
	s_mov_b32 s51, 2
	v_max_f32_e32 v148, v84, v85
	v_max_f32_e32 v149, v68, v69
	v_max3_f32 v148, v148, v86, v87
	v_max3_f32 v149, v149, v70, v71
	v_max3_f32 v148, v148, v88, v89
	v_max3_f32 v149, v149, v72, v73
	v_max3_f32 v148, v148, v90, v91
	v_max3_f32 v149, v149, v74, v75
	v_max3_f32 v148, v148, v92, v93
	v_max3_f32 v149, v149, v76, v77
	v_max3_f32 v148, v148, v94, v95
	v_max3_f32 v149, v149, v78, v79
	v_max3_f32 v148, v148, v96, v97
	v_max3_f32 v149, v149, v80, v81
	v_max3_f32 v148, v148, v98, v99
	v_max3_f32 v149, v149, v82, v83
	v_max_f32_e32 v148, v148, v149
	s_branch .Lmy_attn_yrest
.Lmy_attn_top:
	s_waitcnt lgkmcnt(0)
	s_barrier
	v_mfma_f32_32x32x16_bf16 v[20:35], v[148:151], v[204:207], v[20:35]
	v_mfma_f32_32x32x16_bf16 v[20:35], v[152:155], v[216:219], v[20:35]
	v_fma_f32 v183, v183, v184, v185
	v_max_f32_e32 v148, v84, v85
	v_max_f32_e32 v149, v68, v69
	v_max3_f32 v148, v148, v86, v87
	v_max3_f32 v149, v149, v70, v71
	v_max3_f32 v148, v148, v88, v89
	v_max3_f32 v149, v149, v72, v73
	v_mfma_f32_32x32x16_bf16 v[20:35], v[156:159], v[220:223], v[20:35]
	v_max3_f32 v148, v148, v90, v91
	v_max3_f32 v149, v149, v74, v75
	v_max3_f32 v148, v148, v92, v93
	v_max3_f32 v149, v149, v76, v77
	v_max3_f32 v148, v148, v94, v95
	v_max3_f32 v149, v149, v78, v79
	v_mfma_f32_32x32x16_bf16 v[20:35], v[160:163], v[224:227], v[20:35]
	v_max3_f32 v148, v148, v96, v97
	v_max3_f32 v149, v149, v80, v81
	v_max3_f32 v148, v148, v98, v99
	v_max3_f32 v149, v149, v82, v83
	v_max_f32_e32 v148, v148, v149
.Lmy_attn_yrest:
	v_mov_b32_e32 v149, v148
	s_nop 1
	v_permlane32_swap_b32_e32 v148, v149
	v_max_f32_e32 v148, v148, v149
	v_sub_f32_e32 v149, v148, v182
	v_cmp_ge_f32_e32 vcc, s23, v149
	v_max_f32_e32 v148, v182, v148
	s_cmp_eq_u64 vcc, exec
	s_cselect_b64 vcc, -1, 0
	v_sub_f32_e32 v150, v182, v148
	v_cndmask_b32_e32 v182, v148, v182, vcc
	v_mul_f32_e32 v148, 0xbe0293ee, v182
	v_fmamk_f32 v84, v84, 0x3e0293ee, v148
	v_fmamk_f32 v85, v85, 0x3e0293ee, v148
	v_fmamk_f32 v86, v86, 0x3e0293ee, v148
	v_fmamk_f32 v87, v87, 0x3e0293ee, v148
	v_fmamk_f32 v88, v88, 0x3e0293ee, v148
	v_fmamk_f32 v89, v89, 0x3e0293ee, v148
	v_fmamk_f32 v90, v90, 0x3e0293ee, v148
	v_fmamk_f32 v91, v91, 0x3e0293ee, v148
	v_fmamk_f32 v92, v92, 0x3e0293ee, v148
	v_fmamk_f32 v93, v93, 0x3e0293ee, v148
	v_fmamk_f32 v94, v94, 0x3e0293ee, v148
	v_fmamk_f32 v95, v95, 0x3e0293ee, v148
	v_fmamk_f32 v96, v96, 0x3e0293ee, v148
	v_fmamk_f32 v97, v97, 0x3e0293ee, v148
	v_fmamk_f32 v98, v98, 0x3e0293ee, v148
	v_fmamk_f32 v99, v99, 0x3e0293ee, v148
	v_fmamk_f32 v68, v68, 0x3e0293ee, v148
	v_fmamk_f32 v69, v69, 0x3e0293ee, v148
	v_fmamk_f32 v70, v70, 0x3e0293ee, v148
	v_fmamk_f32 v71, v71, 0x3e0293ee, v148
	v_fmamk_f32 v72, v72, 0x3e0293ee, v148
	v_fmamk_f32 v73, v73, 0x3e0293ee, v148
	v_fmamk_f32 v74, v74, 0x3e0293ee, v148
	v_fmamk_f32 v75, v75, 0x3e0293ee, v148
	v_fmamk_f32 v76, v76, 0x3e0293ee, v148
	v_fmamk_f32 v77, v77, 0x3e0293ee, v148
	v_fmamk_f32 v78, v78, 0x3e0293ee, v148
	v_fmamk_f32 v79, v79, 0x3e0293ee, v148
	v_fmamk_f32 v80, v80, 0x3e0293ee, v148
	v_fmamk_f32 v81, v81, 0x3e0293ee, v148
	v_fmamk_f32 v82, v82, 0x3e0293ee, v148
	v_fmac_f32_e32 v148, 0x3e0293ee, v83
	v_exp_f32_e32 v83, v84
	v_exp_f32_e32 v84, v85
	v_exp_f32_e32 v85, v86
	v_add_f32_e32 v149, v84, v83
	v_exp_f32_e32 v86, v87
	v_add_f32_e32 v149, v85, v149
	v_exp_f32_e32 v87, v88
	v_add_f32_e32 v149, v86, v149
	v_exp_f32_e32 v88, v89
	v_add_f32_e32 v149, v87, v149
	v_exp_f32_e32 v89, v90
	v_add_f32_e32 v149, v88, v149
	v_exp_f32_e32 v90, v91
	v_add_f32_e32 v149, v89, v149
	v_exp_f32_e32 v91, v92
	v_add_f32_e32 v149, v90, v149
	v_exp_f32_e32 v92, v93
	v_add_f32_e32 v149, v91, v149
	v_exp_f32_e32 v93, v94
	v_add_f32_e32 v149, v92, v149
	v_exp_f32_e32 v94, v95
	v_add_f32_e32 v149, v93, v149
	v_exp_f32_e32 v95, v96
	v_add_f32_e32 v149, v94, v149
	v_exp_f32_e32 v96, v97
	v_add_f32_e32 v149, v95, v149
	v_exp_f32_e32 v97, v98
	v_add_f32_e32 v149, v96, v149
	v_exp_f32_e32 v98, v99
	v_add_f32_e32 v149, v97, v149
	v_exp_f32_e32 v99, v148
	v_add_f32_e32 v149, v98, v149
	v_exp_f32_e32 v68, v68
	v_exp_f32_e32 v69, v69
	v_add_f32_e32 v149, v68, v149
	v_exp_f32_e32 v70, v70
	v_add_f32_e32 v149, v69, v149
	v_exp_f32_e32 v71, v71
	v_add_f32_e32 v149, v70, v149
	v_exp_f32_e32 v72, v72
	v_add_f32_e32 v149, v71, v149
	v_exp_f32_e32 v73, v73
	v_add_f32_e32 v149, v72, v149
	v_exp_f32_e32 v74, v74
	v_add_f32_e32 v149, v73, v149
	v_exp_f32_e32 v75, v75
	v_add_f32_e32 v149, v74, v149
	v_exp_f32_e32 v76, v76
	v_add_f32_e32 v149, v75, v149
	v_exp_f32_e32 v77, v77
	v_add_f32_e32 v149, v76, v149
	v_exp_f32_e32 v78, v78
	v_add_f32_e32 v149, v77, v149
	v_exp_f32_e32 v79, v79
	v_add_f32_e32 v149, v78, v149
	v_exp_f32_e32 v80, v80
	v_add_f32_e32 v149, v79, v149
	v_exp_f32_e32 v81, v81
	v_add_f32_e32 v149, v80, v149
	v_exp_f32_e32 v82, v82
	v_add_f32_e32 v149, v81, v149
	v_mul_f32_e32 v150, 0x3e0293ee, v150
	v_add_f32_e32 v149, v82, v149
	v_exp_f32_e32 v150, v150
	v_add_f32_e32 v185, v99, v149
	v_cndmask_b32_e64 v184, v150, 1.0, vcc
	v_cvt_pk_bf16_f32 v148, v83, v84
	v_cvt_pk_bf16_f32 v149, v85, v86
	v_cvt_pk_bf16_f32 v150, v87, v88
	v_cvt_pk_bf16_f32 v151, v89, v90
	v_cvt_pk_bf16_f32 v152, v91, v92
	v_cvt_pk_bf16_f32 v153, v93, v94
	v_cvt_pk_bf16_f32 v154, v95, v96
	v_cvt_pk_bf16_f32 v155, v97, v98
	v_cvt_pk_bf16_f32 v156, v68, v69
	v_cvt_pk_bf16_f32 v157, v70, v71
	v_cvt_pk_bf16_f32 v158, v72, v73
	v_cvt_pk_bf16_f32 v159, v74, v75
	v_cvt_pk_bf16_f32 v160, v76, v77
	v_cvt_pk_bf16_f32 v161, v78, v79
	v_cvt_pk_bf16_f32 v162, v80, v81
	v_cvt_pk_bf16_f32 v163, v82, v99
	s_mov_b32 s53, s52
	s_cbranch_vccnz .LBB0_633
	s_and_saveexec_b64 s[16:17], s[38:39]
	ds_write_b32 v172, v184 offset:128
	s_or_b64 exec, exec, s[16:17]
	s_waitcnt lgkmcnt(0)
	v_add_u32_e32 v80, v171, v168
	ds_read_b128 v[68:71], v80 offset:224
	ds_read_b128 v[72:75], v80 offset:192
	ds_read_b128 v[76:79], v80 offset:160
	ds_read_b128 v[80:83], v80 offset:128
	s_waitcnt lgkmcnt(3)
	v_pk_mul_f32 v[16:17], v[16:17], v[68:69]
	s_waitcnt lgkmcnt(2)
	v_pk_mul_f32 v[12:13], v[12:13], v[72:73]
	s_waitcnt lgkmcnt(1)
	v_pk_mul_f32 v[8:9], v[8:9], v[76:77]
	v_pk_mul_f32 v[18:19], v[18:19], v[70:71]
	v_pk_mul_f32 v[14:15], v[14:15], v[74:75]
	v_pk_mul_f32 v[10:11], v[10:11], v[78:79]
	s_waitcnt lgkmcnt(0)
	v_pk_mul_f32 v[6:7], v[6:7], v[82:83]
	v_pk_mul_f32 v[4:5], v[4:5], v[80:81]
	v_pk_mul_f32 v[64:65], v[64:65], v[68:69]
	v_pk_mul_f32 v[60:61], v[60:61], v[72:73]
	v_pk_mul_f32 v[56:57], v[56:57], v[76:77]
	v_pk_mul_f32 v[66:67], v[66:67], v[70:71]
	v_pk_mul_f32 v[62:63], v[62:63], v[74:75]
	v_pk_mul_f32 v[58:59], v[58:59], v[78:79]
	v_pk_mul_f32 v[54:55], v[54:55], v[82:83]
	v_pk_mul_f32 v[52:53], v[52:53], v[80:81]
	v_pk_mul_f32 v[48:49], v[48:49], v[68:69]
	v_pk_mul_f32 v[44:45], v[44:45], v[72:73]
	v_pk_mul_f32 v[40:41], v[40:41], v[76:77]
	v_pk_mul_f32 v[50:51], v[50:51], v[70:71]
	v_pk_mul_f32 v[46:47], v[46:47], v[74:75]
	v_pk_mul_f32 v[42:43], v[42:43], v[78:79]
	v_pk_mul_f32 v[38:39], v[38:39], v[82:83]
	v_pk_mul_f32 v[36:37], v[36:37], v[80:81]
	v_pk_mul_f32 v[32:33], v[32:33], v[68:69]
	v_pk_mul_f32 v[28:29], v[28:29], v[72:73]
	v_pk_mul_f32 v[24:25], v[24:25], v[76:77]
	v_pk_mul_f32 v[34:35], v[34:35], v[70:71]
	v_pk_mul_f32 v[30:31], v[30:31], v[74:75]
	v_pk_mul_f32 v[26:27], v[26:27], v[78:79]
	v_pk_mul_f32 v[22:23], v[22:23], v[82:83]
	v_pk_mul_f32 v[20:21], v[20:21], v[80:81]
